# v61 + 4096 more FFN2 down conversion items moved from the P7 tail into P11's idle tail round (TAIL_WD2 9216->13312)
# baseline (speedup 1.0000x reference)
.LBB0_1053:
	s_cmpk_lg_i32 s33, 0x100
	s_cbranch_scc1 .Lcv_done
	s_cmpk_lt_i32 s2, 0x80
	s_cbranch_scc1 .Lcv_done
	v_readfirstlane_b32 s4, v0
	v_and_b32_e32 v1, 63, v0
	s_lshr_b32 s4, s4, 6
	s_sub_i32 s5, s2, 0x80
	s_lshl_b32 s5, s5, 3
	s_add_i32 s5, s5, s4
	v_lshrrev_b32_e32 v2, 3, v1
	v_and_b32_e32 v3, 7, v1
	s_lshl_b32 s6, s4, 14
	v_mul_u32_u24_e32 v4, 33, v2
	v_lshl_add_u32 v4, v3, 2, v4
	v_lshl_add_u32 v4, v4, 2, s6
	v_mul_u32_u24_e32 v5, 0x108, v3
	v_add_u32_e32 v5, v5, v2
	v_lshl_add_u32 v5, v5, 2, s6
	v_lshlrev_b32_e32 v78, 4, v3
	v_readlane_b32 s8, v254, 7
	v_readlane_b32 s9, v254, 8
	v_readlane_b32 s10, v254, 9
	v_readlane_b32 s11, v254, 10
	v_readlane_b32 s12, v254, 11
	v_readlane_b32 s13, v254, 12
	s_add_u32 s14, s92, 0x4b800000
	s_addc_u32 s15, s93, 0
	s_add_u32 s36, s92, 0x10300000
	s_addc_u32 s37, s93, 0
	s_mov_b32 s38, 0
	s_cmp_lt_u32 s5, 0x200
	s_movk_i32 s7, 0x1c00
	s_cselect_b32 s7, 0x2000, s7
	s_add_i32 s7, s7, s5
	s_add_i32 s7, s7, 0xe000
	s_cmp_lt_u32 s38, 22
	s_cbranch_scc0 .Lcv_dec_d0
	s_lshl_b32 s39, s38, 10
	s_add_i32 s39, s39, s5
	s_add_i32 s39, s39, 0x5400
	s_mov_b32 s58, 1
	s_cmp_ge_u32 s39, 0x5600
	s_cselect_b32 s43, 0x5600, 0
	s_cselect_b32 s40, s10, s8
	s_cselect_b32 s41, s11, s9
	s_cselect_b32 s42, 0x80, 0
	s_sub_i32 s39, s39, s43
	s_mul_hi_u32 s43, s39, 0x2fa0be83
	s_lshr_b32 s43, s43, 6
	s_mul_i32 s44, s43, 0x158
	s_sub_i32 s44, s39, s44
	s_lshl_b32 s45, s43, 6
	s_lshl_b32 s46, s44, 5
	s_mul_i32 s47, s45, 0x2b00
	s_add_i32 s47, s47, s46
	s_lshl_b32 s47, s47, 2
	s_add_u32 s40, s40, s47
	s_addc_u32 s41, s41, 0
	s_lshr_b32 s48, s46, 7
	s_lshl_b32 s48, s48, 8
	s_and_b32 s49, s46, 0x7f
	s_add_i32 s48, s48, s49
	s_add_i32 s48, s48, s42
	s_lshl_b32 s48, s48, 12
	s_add_i32 s48, s48, s45
	s_lshl_b32 s48, s48, 1
	s_add_u32 s50, s14, s48
	s_addc_u32 s51, s15, 0
	s_mov_b32 s53, 0x56000
	s_mov_b32 s52, 0x10000
	s_mov_b32 s57, 0xac00
	s_movk_i32 s47, 0x2000
	s_branch .Lcv_dec_e0
.Lcv_dec_d0:
	s_sub_i32 s39, s38, 22
	s_lshl_b32 s39, s39, 10
	s_add_i32 s39, s39, s5
	s_add_i32 s39, s39, 0xe000
	s_cmp_le_u32 s39, s7
	s_cselect_b32 s58, 1, 0
	s_min_u32 s39, s39, s7
	s_sub_i32 s39, s39, 0xac00
	s_lshr_b32 s43, s39, 7
	s_and_b32 s44, s39, 0x7f
	s_lshl_b32 s45, s43, 6
	s_lshl_b32 s46, s44, 5
	s_lshl_b32 s47, s45, 12
	s_add_i32 s47, s47, s46
	s_lshl_b32 s47, s47, 2
	s_add_u32 s40, s12, s47
	s_addc_u32 s41, s13, 0
	s_mul_i32 s48, s46, 0x2b00
	s_add_i32 s48, s48, s45
	s_lshl_b32 s48, s48, 1
	s_add_u32 s50, s36, s48
	s_addc_u32 s51, s37, 0
	s_mov_b32 s53, 0x20000
	s_mov_b32 s52, 0x2b000
	s_movk_i32 s57, 0x4000
	s_movk_i32 s47, 0x5600

.Lcv_dec_d1:
	s_sub_i32 s39, s38, 22
	s_lshl_b32 s39, s39, 10
	s_add_i32 s39, s39, s5
	s_add_i32 s39, s39, 0xe000
	s_cmp_le_u32 s39, s7
	s_cselect_b32 s59, 1, 0
	s_min_u32 s39, s39, s7
	s_sub_i32 s39, s39, 0xac00
	s_lshr_b32 s43, s39, 7
	s_and_b32 s44, s39, 0x7f
	s_lshl_b32 s45, s43, 6
	s_lshl_b32 s46, s44, 5
	s_lshl_b32 s47, s45, 12
	s_add_i32 s47, s47, s46
	s_lshl_b32 s47, s47, 2
	s_add_u32 s40, s12, s47
	s_addc_u32 s41, s13, 0
	s_mul_i32 s48, s46, 0x2b00
	s_add_i32 s48, s48, s45
	s_lshl_b32 s48, s48, 1
	s_add_u32 s54, s36, s48
	s_addc_u32 s55, s37, 0
	s_mov_b32 s53, 0x20000
	s_mov_b32 s56, 0x2b000
	s_movk_i32 s57, 0x4000
	s_movk_i32 s47, 0x5600

.LBB0_1344:
	s_cmpk_lg_i32 s33, 0x100
	s_cselect_b64 s[0:1], -1, 0
	s_cmpk_lt_i32 s2, 0xc0
	s_cselect_b64 s[6:7], -1, 0
	s_or_b64 s[0:1], s[6:7], s[0:1]
	s_and_b64 vcc, exec, s[0:1]
	s_cbranch_vccnz .LBB0_1355
	s_ashr_i32 s11, s3, 6
	s_lshl_b32 s12, s2, 3
	s_add_i32 s12, s12, s11
	s_add_i32 s15, s12, 0xfffffa00
	s_cmpk_gt_i32 s15, 0x33ff
	s_waitcnt vmcnt(0)
	s_barrier
	s_cbranch_scc1 .LBB0_1355
	s_sub_i32 s0, 0x33ff, s15
	s_ashr_i32 s1, s0, 31
	s_lshr_b32 s1, s1, 23
	s_add_i32 s0, s0, s1
	s_and_b32 s16, s0, 0xfffffe00
	s_cmp_lt_i32 s16, 0
	s_cbranch_scc1 .LBB0_1355
	s_lshl_b32 s1, s11, 14
	s_add_i32 s13, s1, 0
	s_ashr_i32 s1, s15, 31
	s_lshr_b32 s1, s1, 25
	s_add_i32 s1, s15, s1
	v_bfe_u32 v134, v1, 3, 3
	s_ashr_i32 s1, s1, 7
	v_lshl_or_b32 v2, s1, 6, v134
	v_readlane_b32 s20, v254, 7
	v_ashrrev_i32_e32 v3, 31, v2
	v_readlane_b32 s21, v254, 8
	v_readlane_b32 s22, v254, 9
	v_readlane_b32 s23, v254, 10
	v_readlane_b32 s24, v254, 11
	v_readlane_b32 s25, v254, 12
	s_lshl_b32 s1, s1, 12
	s_lshl_b32 s3, s15, 5
	v_lshlrev_b64 v[2:3], 14, v[2:3]
	v_readlane_b32 s26, v254, 13
	v_readlane_b32 s27, v254, 14
	s_mov_b64 s[20:21], s[24:25]
	s_sub_i32 s6, s3, s1
	v_and_b32_e32 v1, 7, v1
	v_lshl_add_u64 v[2:3], s[20:21], 0, v[2:3]
	s_ashr_i32 s7, s6, 31
	v_mov_b32_e32 v131, 0
	v_lshl_add_u64 v[2:3], s[6:7], 2, v[2:3]
	v_lshlrev_b32_e32 v130, 4, v1
	v_lshl_add_u64 v[26:27], v[2:3], 0, v[130:131]
	s_mov_b32 s1, 0x20000
	v_add_co_u32_e32 v10, vcc, s1, v26
	s_mov_b32 s3, 0x40000
	s_nop 0
	v_addc_co_u32_e32 v11, vcc, 0, v27, vcc
	v_add_co_u32_e32 v18, vcc, s3, v26
	s_mov_b32 s6, 0x60000
	s_nop 0
	v_addc_co_u32_e32 v19, vcc, 0, v27, vcc
	v_add_co_u32_e32 v20, vcc, s6, v26
	s_mov_b32 s7, 0x80000
	s_nop 0
	v_addc_co_u32_e32 v21, vcc, 0, v27, vcc
	s_add_i32 s0, s16, s15
	v_add_co_u32_e32 v28, vcc, s7, v26
	s_add_i32 s17, s15, 0x400
	s_nop 0
	v_addc_co_u32_e32 v29, vcc, 0, v27, vcc
	s_mov_b32 s8, 0xa0000
	s_cmpk_gt_u32 s16, 0x400
	v_add_co_u32_e32 v30, vcc, s8, v26
	s_cselect_b32 s16, s17, s0
	s_nop 0
	v_addc_co_u32_e32 v31, vcc, 0, v27, vcc
	s_mov_b32 s9, 0xc0000
	s_ashr_i32 s17, s16, 31
	v_add_co_u32_e32 v34, vcc, s9, v26
	s_lshr_b32 s17, s17, 25
	s_nop 0
	v_addc_co_u32_e32 v35, vcc, 0, v27, vcc
	s_mov_b32 s10, 0xe0000
	s_add_i32 s17, s16, s17
	v_add_co_u32_e32 v36, vcc, s10, v26
	s_ashr_i32 s17, s17, 7
	global_load_dwordx4 v[2:5], v[26:27], off
	global_load_dwordx4 v[6:9], v[10:11], off
	s_nop 0
	global_load_dwordx4 v[10:13], v[18:19], off
	global_load_dwordx4 v[14:17], v[20:21], off
	s_nop 0
	global_load_dwordx4 v[18:21], v[28:29], off
	global_load_dwordx4 v[22:25], v[30:31], off
	v_addc_co_u32_e32 v37, vcc, 0, v27, vcc
	global_load_dwordx4 v[26:29], v[34:35], off
	global_load_dwordx4 v[30:33], v[36:37], off
	v_lshl_or_b32 v34, s17, 6, v134
	v_ashrrev_i32_e32 v35, 31, v34
	s_lshl_b32 s17, s17, 12
	s_lshl_b32 s16, s16, 5
	v_lshlrev_b64 v[34:35], 14, v[34:35]
	s_sub_i32 s16, s16, s17
	v_lshl_add_u64 v[34:35], s[20:21], 0, v[34:35]
	s_ashr_i32 s17, s16, 31
	v_lshl_add_u64 v[34:35], s[16:17], 2, v[34:35]
	v_lshl_add_u64 v[66:67], v[34:35], 0, v[130:131]
	v_add_co_u32_e32 v68, vcc, s10, v66
	s_addk_i32 s15, 0x200
	s_nop 0
	v_addc_co_u32_e32 v69, vcc, 0, v67, vcc
	v_add_co_u32_e32 v38, vcc, s9, v66
	s_min_i32 s15, s15, s0
	s_nop 0
	v_addc_co_u32_e32 v39, vcc, 0, v67, vcc
	v_add_co_u32_e32 v40, vcc, s8, v66
	s_ashr_i32 s16, s15, 31
	s_nop 0
	v_addc_co_u32_e32 v41, vcc, 0, v67, vcc
	v_add_co_u32_e32 v46, vcc, s7, v66
	s_lshr_b32 s16, s16, 25
	s_nop 0
	v_addc_co_u32_e32 v47, vcc, 0, v67, vcc
	v_add_co_u32_e32 v48, vcc, s6, v66
	s_add_i32 s16, s15, s16
	s_nop 0
	v_addc_co_u32_e32 v49, vcc, 0, v67, vcc
	v_add_co_u32_e32 v70, vcc, s3, v66
	s_ashr_i32 s16, s16, 7
	s_nop 0
	v_addc_co_u32_e32 v71, vcc, 0, v67, vcc
	v_add_co_u32_e32 v72, vcc, s1, v66
	global_load_dwordx4 v[42:45], v[38:39], off
	global_load_dwordx4 v[34:37], v[40:41], off
	global_load_dwordx4 v[50:53], v[46:47], off
	s_nop 0
	global_load_dwordx4 v[38:41], v[48:49], off
	v_addc_co_u32_e32 v73, vcc, 0, v67, vcc
	global_load_dwordx4 v[58:61], v[70:71], off
	global_load_dwordx4 v[46:49], v[72:73], off
	global_load_dwordx4 v[62:65], v[68:69], off
	global_load_dwordx4 v[54:57], v[66:67], off
	v_lshl_or_b32 v66, s16, 6, v134
	v_ashrrev_i32_e32 v67, 31, v66
	s_lshl_b32 s16, s16, 12
	s_lshl_b32 s15, s15, 5
	v_lshlrev_b64 v[66:67], 14, v[66:67]
	s_sub_i32 s16, s15, s16
	v_lshl_add_u64 v[66:67], s[20:21], 0, v[66:67]
	s_ashr_i32 s17, s16, 31
	v_lshl_add_u64 v[66:67], s[16:17], 2, v[66:67]
	v_lshl_add_u64 v[98:99], v[66:67], 0, v[130:131]
	v_add_co_u32_e32 v100, vcc, s10, v98
	s_lshl_b32 s11, s11, 5
	s_nop 0
	v_addc_co_u32_e32 v101, vcc, 0, v99, vcc
	v_add_co_u32_e32 v70, vcc, s9, v98
	v_readlane_b32 s16, v255, 1
	s_nop 0
	v_addc_co_u32_e32 v71, vcc, 0, v99, vcc
	v_add_co_u32_e32 v72, vcc, s8, v98
	v_readlane_b32 s17, v255, 2
	s_nop 0
	v_addc_co_u32_e32 v73, vcc, 0, v99, vcc
	v_add_co_u32_e32 v78, vcc, s7, v98
	global_load_dwordx4 v[74:77], v[70:71], off
	global_load_dwordx4 v[66:69], v[72:73], off
	v_addc_co_u32_e32 v79, vcc, 0, v99, vcc
	v_add_co_u32_e32 v80, vcc, s6, v98
	v_lshl_add_u64 v[132:133], s[16:17], 0, v[130:131]
	s_nop 0
	v_addc_co_u32_e32 v81, vcc, 0, v99, vcc
	v_add_co_u32_e32 v102, vcc, s3, v98
	global_load_dwordx4 v[86:89], v[78:79], off
	global_load_dwordx4 v[70:73], v[80:81], off
	v_addc_co_u32_e32 v103, vcc, 0, v99, vcc
	v_add_co_u32_e32 v104, vcc, s1, v98
	s_mov_b64 s[22:23], s[26:27]
	s_nop 0
	v_addc_co_u32_e32 v105, vcc, 0, v99, vcc
	global_load_dwordx4 v[90:93], v[102:103], off
	global_load_dwordx4 v[78:81], v[104:105], off
	global_load_dwordx4 v[94:97], v[100:101], off
	global_load_dwordx4 v[82:85], v[98:99], off
	v_lshlrev_b32_e32 v98, 2, v1
	v_mul_u32_u24_e32 v1, 0x420, v1
	v_lshlrev_b32_e32 v101, 2, v134
	v_add_u32_e32 v99, s13, v130
	v_add3_u32 v1, s13, v1, v101
	s_lshl_b32 s13, s2, 8
	s_add_i32 s13, s13, s11
	v_mul_u32_u24_e32 v100, 0x84, v134
	v_or_b32_e32 v101, s13, v134
	v_add_u32_e32 v135, 0xffff4000, v101
	s_add_i32 s11, s12, 0x600
	v_lshlrev_b32_e32 v130, 2, v98
	s_movk_i32 s12, 0x5600
	v_add_u32_e32 v136, v99, v100
	s_branch .LBB0_1349
